# v_li + M1 row-major accumulator layout: MFMA operands swapped, W rows fetched as n=4*idx+blk, coalesced dwordx2 epilogue stores
# speedup vs baseline: 1.0151x; 1.0021x over previous
.LBB0_931:
	s_or_b64 exec, exec, s[2:3]
	v_readlane_b32 s12, v253, 35
	s_mov_b32 s8, s87
	s_mov_b32 s6, s87
	s_mov_b32 s2, s87
	s_mov_b32 s4, s87
	s_waitcnt lgkmcnt(0)
	v_mov_b32_e32 v2, v0
	v_readlane_b32 s13, v253, 36
	s_barrier
	s_lshl_b32 s36, s46, 22
	s_movk_i32 s11, 0x400
	v_readfirstlane_b32 s10, v2
	s_andn2_b64 vcc, exec, s[12:13]
	s_cbranch_vccnz .LBB0_962
	v_lshlrev_b32_e32 v5, 4, v2
	v_add_u32_e32 v6, 0x2000, v5
	s_ashr_i32 s9, s8, 31
	v_ashrrev_i32_e32 v3, 31, v6
	s_lshl_b64 s[8:9], s[8:9], 3
	v_lshrrev_b32_e32 v3, 22, v3
	s_add_u32 s8, s0, s8
	v_add_u32_e32 v3, v6, v3
	s_addc_u32 s9, s1, s9
	v_ashrrev_i32_e32 v3, 10, v3
	s_mov_b64 s[8:9], s[100:101]
	v_mul_i32_i24_e32 v7, 0x400, v3
	v_sub_u32_e32 v6, v6, v7
	v_lshrrev_b32_e32 v7, 4, v6
	v_bitop3_b32 v7, v7, v6, 32 bitop3:0x6c
	v_ashrrev_i32_e32 v6, 31, v7
	s_waitcnt lgkmcnt(0)
	s_add_u32 s3, s8, s89
	v_lshrrev_b32_e32 v6, 26, v6
	s_addc_u32 s5, s9, 0
	v_add_u32_e32 v8, v7, v6
	v_lshlrev_b32_e32 v10, 3, v3
	s_add_u32 s37, s3, 0x7600000
	v_ashrrev_i32_e32 v6, 6, v8
	v_and_b32_e32 v10, -16, v10
	s_addc_u32 s38, s5, 0
	s_ashr_i32 s7, s6, 31
	v_add_u32_e32 v10, v6, v10
	s_lshl_b64 s[6:7], s[6:7], 3
	v_lshrrev_b32_e32 v11, 2, v10
	v_lshlrev_b32_e32 v12, 1, v10
	v_and_b32_e32 v8, 0xc0, v8
	s_add_u32 s6, s0, s6
	v_and_b32_e32 v9, 3, v6
	v_and_b32_e32 v11, 4, v11
	v_and_b32_e32 v12, 0x1fffd8, v12
	v_sub_u32_e32 v7, v7, v8
	s_addc_u32 s7, s1, s7
	v_and_b32_e32 v9, 15, v10
	v_bfe_u32 v11, v10, 4, 1
	v_lshl_or_b32 v9, v9, 2, v11
	v_lshrrev_b32_e32 v11, 5, v10
	v_lshl_or_b32 v9, v11, 6, v9
	v_lshlrev_b32_e32 v11, 5, v3
	v_ashrrev_i16_sdwa v7, v238, sext(v7) dst_sel:DWORD dst_unused:UNUSED_PAD src0_sel:DWORD src1_sel:BYTE_0
	s_mov_b64 s[6:7], s[100:101]
	v_and_b32_e32 v11, 32, v11
	v_bfe_i32 v7, v7, 0, 16
	v_add_lshl_u32 v8, v11, v7, 1
	v_lshl_add_u32 v198, v9, 11, v8
	v_lshl_add_u32 v200, v10, 11, v8
	v_bfe_i32 v8, v2, 27, 1
	v_lshrrev_b32_e32 v8, 22, v8
	s_lshl_b32 s3, s36, 1
	v_add_u32_e32 v8, v5, v8
	s_waitcnt lgkmcnt(0)
	s_add_u32 s3, s6, s3
	v_and_b32_e32 v8, 0xfffffc00, v8
	s_addc_u32 s5, s7, 0
	v_sub_u32_e32 v5, v5, v8
	s_add_u32 s39, s3, 0x2600000
	v_lshrrev_b32_e32 v8, 4, v5
	v_ashrrev_i32_e32 v9, 31, v2
	s_addc_u32 s40, s5, 0
	s_ashr_i32 s3, s2, 31
	v_bitop3_b32 v5, v8, v5, 32 bitop3:0x6c
	v_lshrrev_b32_e32 v9, 26, v9
	s_lshl_b64 s[2:3], s[2:3], 3
	v_ashrrev_i32_e32 v8, 31, v5
	v_add_u32_e32 v9, v2, v9
	s_add_u32 s2, s0, s2
	v_lshrrev_b32_e32 v8, 26, v8
	v_ashrrev_i32_e32 v9, 6, v9
	s_addc_u32 s3, s1, s3
	s_ashr_i32 s5, s4, 31
	v_add_u32_e32 v10, v5, v8
	v_lshlrev_b32_e32 v12, 3, v9
	s_lshl_b64 s[4:5], s[4:5], 3
	v_ashrrev_i32_e32 v8, 6, v10
	v_and_b32_e32 v12, -16, v12
	s_add_u32 s4, s0, s4
	v_add_u32_e32 v12, v8, v12
	s_addc_u32 s5, s1, s5
	s_ashr_i32 s13, s10, 6
	v_lshrrev_b32_e32 v13, 2, v12
	v_lshlrev_b32_e32 v14, 1, v12
	v_and_b32_e32 v10, 0xc0, v10
	s_ashr_i32 s12, s10, 8
	s_lshl_b32 s6, s13, 10
	v_and_b32_e32 v11, 3, v8
	v_and_b32_e32 v13, 4, v13
	v_and_b32_e32 v14, 0x1fffd8, v14
	v_sub_u32_e32 v5, v5, v10
	v_readlane_b32 s8, v253, 56
	v_and_b32_e32 v11, 15, v12
	v_bfe_u32 v13, v12, 4, 1
	v_lshl_or_b32 v11, v11, 2, v13
	v_lshrrev_b32_e32 v13, 5, v12
	v_lshl_or_b32 v11, v13, 6, v11
	v_lshlrev_b32_e32 v13, 5, v9
	v_ashrrev_i16_sdwa v5, v238, sext(v5) dst_sel:DWORD dst_unused:UNUSED_PAD src0_sel:DWORD src1_sel:BYTE_0
	v_readlane_b32 s9, v253, 57
	s_add_u32 s22, s39, s8
	v_and_b32_e32 v13, 32, v13
	v_bfe_i32 v10, v5, 0, 16
	s_addc_u32 s23, s40, s9
	s_add_i32 s41, s6, 0
	v_add_lshl_u32 v5, v13, v10, 1
	s_add_i32 s42, s41, 0x10000
	s_add_i32 s43, s41, 0x12000
	v_lshl_add_u32 v202, v11, 11, v5
	s_mov_b32 m0, s42
	s_add_u32 s6, s22, 0x1000
	global_load_lds_dwordx4 v202, s[22:23]
	s_mov_b32 m0, s43
	s_addc_u32 s7, s23, 0
	s_add_i32 s44, s41, 0x14000
	global_load_lds_dwordx4 v198, s[22:23]
	s_mov_b32 m0, s44
	s_add_i32 s45, s41, 0x16000
	global_load_lds_dwordx4 v202, s[6:7]
	s_mov_b32 m0, s45
	v_lshl_add_u32 v204, v12, 11, v5
	global_load_lds_dwordx4 v198, s[6:7]
	v_readlane_b32 s6, v253, 52
	v_readlane_b32 s7, v253, 53
	s_add_u32 s24, s37, s6
	s_addc_u32 s25, s38, s7
	s_add_i32 s46, s41, 0x2000
	s_mov_b32 m0, s41
	s_add_u32 s6, s24, 0x40000
	global_load_lds_dwordx4 v204, s[24:25]
	s_mov_b32 m0, s46
	s_addc_u32 s7, s25, 0
	s_add_i32 s47, s41, 0x4000
	v_mov_b32_e32 v203, v4
	global_load_lds_dwordx4 v200, s[24:25]
	s_mov_b32 m0, s47
	s_add_i32 s48, s41, 0x6000
	v_lshl_add_u64 v[12:13], s[22:23], 0, v[202:203]
	v_mov_b32_e32 v199, v4
	global_load_lds_dwordx4 v204, s[6:7]
	s_mov_b32 m0, s48
	s_add_i32 s49, s41, 0x18000
	v_lshl_add_u64 v[14:15], s[22:23], 0, v[198:199]
	v_mov_b32_e32 v205, v4
	global_load_lds_dwordx4 v200, s[6:7]
	v_lshl_add_u64 v[12:13], v[12:13], 0, s[68:69]
	s_mov_b32 m0, s49
	s_add_i32 s50, s41, 0x1a000
	v_lshl_add_u64 v[16:17], s[24:25], 0, v[204:205]
	v_mov_b32_e32 v201, v4
	global_load_lds_dwordx4 v[12:13], off
	v_lshl_add_u64 v[12:13], v[14:15], 0, s[68:69]
	s_mov_b32 m0, s50
	s_add_i32 s51, s41, 0x8000
	s_add_i32 s52, s41, 0xa000
	v_lshl_add_u64 v[18:19], s[24:25], 0, v[200:201]
	global_load_lds_dwordx4 v[12:13], off
	v_lshl_add_u64 v[12:13], v[16:17], 0, s[68:69]
	s_mov_b32 m0, s51
	s_add_u32 s6, s22, 0x1080
	global_load_lds_dwordx4 v[12:13], off
	v_lshl_add_u64 v[12:13], v[18:19], 0, s[68:69]
	s_mov_b32 m0, s52
	s_addc_u32 s7, s23, 0
	s_add_i32 s53, s41, 0x1c000
	global_load_lds_dwordx4 v[12:13], off
	s_mov_b32 m0, s53
	s_add_i32 s54, s41, 0x1e000
	global_load_lds_dwordx4 v202, s[6:7]
	s_mov_b32 m0, s54
	s_cmp_eq_u32 s12, 1
	global_load_lds_dwordx4 v198, s[6:7]
	s_mov_b64 s[8:9], s[100:101]
	s_mov_b64 s[6:7], s[100:101]
	s_cselect_b64 s[2:3], -1, 0
	s_cmp_lg_u32 s12, 1
	s_cbranch_scc1 .LBB0_934
	s_barrier

.LBB0_941:
	s_waitcnt lgkmcnt(0)
	s_add_i32 s65, s65, 2
	s_barrier
	s_setprio 1
	s_waitcnt lgkmcnt(0)
	v_mfma_f32_16x16x32_bf16 v[66:69], v[190:193], v[150:153], v[66:69]
	v_mfma_f32_16x16x32_bf16 v[62:65], v[190:193], v[158:161], v[62:65]
	v_mfma_f32_16x16x32_bf16 v[50:53], v[182:185], v[150:153], v[50:53]
	v_mfma_f32_16x16x32_bf16 v[46:49], v[182:185], v[158:161], v[46:49]
	v_mfma_f32_16x16x32_bf16 v[34:37], v[174:177], v[150:153], v[34:37]
	v_mfma_f32_16x16x32_bf16 v[30:33], v[174:177], v[158:161], v[30:33]
	v_mfma_f32_16x16x32_bf16 v[18:21], v[166:169], v[150:153], v[18:21]
	v_mfma_f32_16x16x32_bf16 v[14:17], v[166:169], v[158:161], v[14:17]
	v_mfma_f32_16x16x32_bf16 v[66:69], v[194:197], v[154:157], v[66:69]
	v_mfma_f32_16x16x32_bf16 v[62:65], v[194:197], v[162:165], v[62:65]
	v_mfma_f32_16x16x32_bf16 v[50:53], v[186:189], v[154:157], v[50:53]
	v_mfma_f32_16x16x32_bf16 v[46:49], v[186:189], v[162:165], v[46:49]
	v_mfma_f32_16x16x32_bf16 v[34:37], v[178:181], v[154:157], v[34:37]
	v_mfma_f32_16x16x32_bf16 v[30:33], v[178:181], v[162:165], v[30:33]
	v_mfma_f32_16x16x32_bf16 v[18:21], v[170:173], v[154:157], v[18:21]
	v_mfma_f32_16x16x32_bf16 v[14:17], v[170:173], v[162:165], v[14:17]
	s_setprio 0
	s_setprio 1
	v_mfma_f32_16x16x32_bf16 v[58:61], v[190:193], v[134:137], v[58:61]
	v_mfma_f32_16x16x32_bf16 v[54:57], v[190:193], v[142:145], v[54:57]
	v_mfma_f32_16x16x32_bf16 v[42:45], v[182:185], v[134:137], v[42:45]
	v_mfma_f32_16x16x32_bf16 v[38:41], v[182:185], v[142:145], v[38:41]
	v_mfma_f32_16x16x32_bf16 v[26:29], v[174:177], v[134:137], v[26:29]
	v_mfma_f32_16x16x32_bf16 v[22:25], v[174:177], v[142:145], v[22:25]
	v_mfma_f32_16x16x32_bf16 v[10:13], v[166:169], v[134:137], v[10:13]
	v_mfma_f32_16x16x32_bf16 v[6:9], v[166:169], v[142:145], v[6:9]
	v_mfma_f32_16x16x32_bf16 v[58:61], v[194:197], v[138:141], v[58:61]
	v_mfma_f32_16x16x32_bf16 v[54:57], v[194:197], v[146:149], v[54:57]
	v_mfma_f32_16x16x32_bf16 v[42:45], v[186:189], v[138:141], v[42:45]
	v_mfma_f32_16x16x32_bf16 v[38:41], v[186:189], v[146:149], v[38:41]
	v_mfma_f32_16x16x32_bf16 v[26:29], v[178:181], v[138:141], v[26:29]
	v_mfma_f32_16x16x32_bf16 v[22:25], v[178:181], v[146:149], v[22:25]
	v_mfma_f32_16x16x32_bf16 v[10:13], v[170:173], v[138:141], v[10:13]
	v_mfma_f32_16x16x32_bf16 v[6:9], v[170:173], v[146:149], v[6:9]
	s_setprio 0
	s_barrier
	s_add_u32 s63, s63, 0x100
	s_addc_u32 s64, s64, 0
	s_add_u32 s22, s22, 0x100
	s_addc_u32 s23, s23, 0
	s_cmp_ge_i32 s65, s55
	s_cbranch_scc1 .LBB0_952
.LBB0_942:
	v_add_u32_e32 v134, 0x10000, v227
	v_add_u32_e32 v146, 0x14000, v227
	ds_read_b128 v[150:153], v134
	ds_read_b128 v[154:157], v134 offset:1024
	ds_read_b128 v[158:161], v134 offset:2048
	ds_read_b128 v[162:165], v134 offset:3072
	ds_read_b128 v[134:137], v146
	ds_read_b128 v[138:141], v146 offset:1024
	ds_read_b128 v[142:145], v146 offset:2048
	ds_read_b128 v[146:149], v146 offset:3072
	s_cmp_lg_u32 s56, s65
	s_cselect_b64 s[28:29], -1, 0
	s_add_u32 s26, s22, 0xfffc0080
	s_addc_u32 s27, s23, -1
	s_and_b64 s[24:25], s[28:29], exec
	s_cselect_b32 s27, s27, s13
	s_cselect_b32 s26, s26, s15
	s_cselect_b32 s25, s64, s61
	s_cselect_b32 s24, s63, s62
	v_lshl_add_u64 v[218:219], s[22:23], 0, v[206:207]
	s_add_i32 m0, s41, 0xc000
	ds_read_b128 v[166:169], v228
	ds_read_b128 v[170:173], v228 offset:1024
	ds_read_b128 v[174:177], v228 offset:2048
	ds_read_b128 v[178:181], v228 offset:3072
	ds_read_b128 v[182:185], v228 offset:4096
	ds_read_b128 v[186:189], v228 offset:5120
	ds_read_b128 v[190:193], v228 offset:6144
	ds_read_b128 v[194:197], v228 offset:7168
	global_load_lds_dwordx4 v[218:219], off
	v_lshl_add_u64 v[218:219], s[22:23], 0, v[208:209]
	s_add_i32 m0, s41, 0xe000
	s_nop 0
	global_load_lds_dwordx4 v[218:219], off
	s_waitcnt vmcnt(8)
	s_waitcnt lgkmcnt(0)
	s_barrier
	s_setprio 1
	s_waitcnt lgkmcnt(0)
	v_mfma_f32_16x16x32_bf16 v[130:133], v[166:169], v[150:153], v[130:133]
	v_mfma_f32_16x16x32_bf16 v[126:129], v[166:169], v[158:161], v[126:129]
	v_mfma_f32_16x16x32_bf16 v[114:117], v[174:177], v[150:153], v[114:117]
	v_mfma_f32_16x16x32_bf16 v[110:113], v[174:177], v[158:161], v[110:113]
	v_mfma_f32_16x16x32_bf16 v[98:101], v[182:185], v[150:153], v[98:101]
	v_mfma_f32_16x16x32_bf16 v[94:97], v[182:185], v[158:161], v[94:97]
	v_mfma_f32_16x16x32_bf16 v[82:85], v[190:193], v[150:153], v[82:85]
	v_mfma_f32_16x16x32_bf16 v[78:81], v[190:193], v[158:161], v[78:81]
	v_mfma_f32_16x16x32_bf16 v[130:133], v[170:173], v[154:157], v[130:133]
	v_mfma_f32_16x16x32_bf16 v[126:129], v[170:173], v[162:165], v[126:129]
	v_mfma_f32_16x16x32_bf16 v[114:117], v[178:181], v[154:157], v[114:117]
	v_mfma_f32_16x16x32_bf16 v[110:113], v[178:181], v[162:165], v[110:113]
	v_mfma_f32_16x16x32_bf16 v[98:101], v[186:189], v[154:157], v[98:101]
	v_mfma_f32_16x16x32_bf16 v[94:97], v[186:189], v[162:165], v[94:97]
	v_mfma_f32_16x16x32_bf16 v[82:85], v[194:197], v[154:157], v[82:85]
	v_mfma_f32_16x16x32_bf16 v[78:81], v[194:197], v[162:165], v[78:81]
	s_setprio 0
	s_setprio 1
	v_mfma_f32_16x16x32_bf16 v[122:125], v[166:169], v[134:137], v[122:125]
	v_mfma_f32_16x16x32_bf16 v[118:121], v[166:169], v[142:145], v[118:121]
	v_mfma_f32_16x16x32_bf16 v[106:109], v[174:177], v[134:137], v[106:109]
	v_mfma_f32_16x16x32_bf16 v[102:105], v[174:177], v[142:145], v[102:105]
	v_mfma_f32_16x16x32_bf16 v[90:93], v[182:185], v[134:137], v[90:93]
	v_mfma_f32_16x16x32_bf16 v[86:89], v[182:185], v[142:145], v[86:89]
	v_mfma_f32_16x16x32_bf16 v[74:77], v[190:193], v[134:137], v[74:77]
	v_mfma_f32_16x16x32_bf16 v[70:73], v[190:193], v[142:145], v[70:73]
	v_mfma_f32_16x16x32_bf16 v[122:125], v[170:173], v[138:141], v[122:125]
	v_mfma_f32_16x16x32_bf16 v[118:121], v[170:173], v[146:149], v[118:121]
	v_mfma_f32_16x16x32_bf16 v[106:109], v[178:181], v[138:141], v[106:109]
	v_mfma_f32_16x16x32_bf16 v[102:105], v[178:181], v[146:149], v[102:105]
	v_mfma_f32_16x16x32_bf16 v[90:93], v[186:189], v[138:141], v[90:93]
	v_mfma_f32_16x16x32_bf16 v[86:89], v[186:189], v[146:149], v[86:89]
	v_mfma_f32_16x16x32_bf16 v[74:77], v[194:197], v[138:141], v[74:77]
	v_mfma_f32_16x16x32_bf16 v[70:73], v[194:197], v[146:149], v[70:73]
	s_setprio 0
	s_barrier
	ds_read_b128 v[190:193], v228 offset:16384
	ds_read_b128 v[194:197], v228 offset:17408
	ds_read_b128 v[182:185], v228 offset:18432
	ds_read_b128 v[186:189], v228 offset:19456
	ds_read_b128 v[174:177], v228 offset:20480
	ds_read_b128 v[178:181], v228 offset:21504
	ds_read_b128 v[166:169], v228 offset:22528
	ds_read_b128 v[170:173], v228 offset:23552
	s_or_b64 s[28:29], s[20:21], s[28:29]
	s_xor_b64 s[30:31], s[28:29], -1
	s_mov_b64 s[34:35], -1
	s_and_b64 vcc, exec, s[30:31]
	s_cbranch_vccz .LBB0_944
	s_waitcnt vmcnt(2)
	s_mov_b64 s[34:35], 0
.LBB0_944:
	s_andn2_b64 vcc, exec, s[34:35]
	v_lshl_add_u64 v[224:225], s[24:25], 0, v[202:203]
	v_lshl_add_u64 v[222:223], s[24:25], 0, v[198:199]
	v_lshl_add_u64 v[220:221], s[26:27], 0, v[204:205]
	v_lshl_add_u64 v[218:219], s[26:27], 0, v[200:201]
	s_cbranch_vccnz .LBB0_946
	s_mov_b32 m0, s42
	s_add_u32 s34, s24, 0x1000
	global_load_lds_dwordx4 v[224:225], off
	s_mov_b32 m0, s43
	s_addc_u32 s35, s25, 0
	global_load_lds_dwordx4 v[222:223], off
	v_lshl_add_u64 v[244:245], s[34:35], 0, v[202:203]
	s_mov_b32 m0, s44
	s_nop 0
	global_load_lds_dwordx4 v[244:245], off
	v_lshl_add_u64 v[244:245], s[34:35], 0, v[198:199]
	s_mov_b32 m0, s45
	s_nop 0
	global_load_lds_dwordx4 v[244:245], off
	s_mov_b32 m0, s41
	s_nop 0
	global_load_lds_dwordx4 v[220:221], off
	s_mov_b32 m0, s46
	s_nop 0
	global_load_lds_dwordx4 v[218:219], off
	s_waitcnt vmcnt(8)
.LBB0_946:
	s_waitcnt lgkmcnt(0)
	s_barrier
	s_setprio 1
	s_waitcnt lgkmcnt(0)
	v_mfma_f32_16x16x32_bf16 v[66:69], v[190:193], v[150:153], v[66:69]
	v_mfma_f32_16x16x32_bf16 v[62:65], v[190:193], v[158:161], v[62:65]
	v_mfma_f32_16x16x32_bf16 v[50:53], v[182:185], v[150:153], v[50:53]
	v_mfma_f32_16x16x32_bf16 v[46:49], v[182:185], v[158:161], v[46:49]
	v_mfma_f32_16x16x32_bf16 v[34:37], v[174:177], v[150:153], v[34:37]
	v_mfma_f32_16x16x32_bf16 v[30:33], v[174:177], v[158:161], v[30:33]
	v_mfma_f32_16x16x32_bf16 v[18:21], v[166:169], v[150:153], v[18:21]
	v_mfma_f32_16x16x32_bf16 v[14:17], v[166:169], v[158:161], v[14:17]
	v_mfma_f32_16x16x32_bf16 v[66:69], v[194:197], v[154:157], v[66:69]
	v_mfma_f32_16x16x32_bf16 v[62:65], v[194:197], v[162:165], v[62:65]
	v_mfma_f32_16x16x32_bf16 v[50:53], v[186:189], v[154:157], v[50:53]
	v_mfma_f32_16x16x32_bf16 v[46:49], v[186:189], v[162:165], v[46:49]
	v_mfma_f32_16x16x32_bf16 v[34:37], v[178:181], v[154:157], v[34:37]
	v_mfma_f32_16x16x32_bf16 v[30:33], v[178:181], v[162:165], v[30:33]
	v_mfma_f32_16x16x32_bf16 v[18:21], v[170:173], v[154:157], v[18:21]
	v_mfma_f32_16x16x32_bf16 v[14:17], v[170:173], v[162:165], v[14:17]
	s_setprio 0
	s_setprio 1
	v_mfma_f32_16x16x32_bf16 v[58:61], v[190:193], v[134:137], v[58:61]
	v_mfma_f32_16x16x32_bf16 v[54:57], v[190:193], v[142:145], v[54:57]
	v_mfma_f32_16x16x32_bf16 v[42:45], v[182:185], v[134:137], v[42:45]
	v_mfma_f32_16x16x32_bf16 v[38:41], v[182:185], v[142:145], v[38:41]
	v_mfma_f32_16x16x32_bf16 v[26:29], v[174:177], v[134:137], v[26:29]
	v_mfma_f32_16x16x32_bf16 v[22:25], v[174:177], v[142:145], v[22:25]
	v_mfma_f32_16x16x32_bf16 v[10:13], v[166:169], v[134:137], v[10:13]
	v_mfma_f32_16x16x32_bf16 v[6:9], v[166:169], v[142:145], v[6:9]
	v_mfma_f32_16x16x32_bf16 v[58:61], v[194:197], v[138:141], v[58:61]
	v_mfma_f32_16x16x32_bf16 v[54:57], v[194:197], v[146:149], v[54:57]
	v_mfma_f32_16x16x32_bf16 v[42:45], v[186:189], v[138:141], v[42:45]
	v_mfma_f32_16x16x32_bf16 v[38:41], v[186:189], v[146:149], v[38:41]
	v_mfma_f32_16x16x32_bf16 v[26:29], v[178:181], v[138:141], v[26:29]
	v_mfma_f32_16x16x32_bf16 v[22:25], v[178:181], v[146:149], v[22:25]
	v_mfma_f32_16x16x32_bf16 v[10:13], v[170:173], v[138:141], v[10:13]
	v_mfma_f32_16x16x32_bf16 v[6:9], v[170:173], v[146:149], v[6:9]
	s_setprio 0
	s_barrier
	v_add_u32_e32 v134, 0x18000, v227
	v_add_u32_e32 v146, 0x1c000, v227
	ds_read_b128 v[150:153], v134
	ds_read_b128 v[154:157], v134 offset:1024
	ds_read_b128 v[158:161], v134 offset:2048
	ds_read_b128 v[162:165], v134 offset:3072
	ds_read_b128 v[134:137], v146
	ds_read_b128 v[138:141], v146 offset:1024
	ds_read_b128 v[142:145], v146 offset:2048
	ds_read_b128 v[146:149], v146 offset:3072
	ds_read_b128 v[190:193], v228 offset:32768
	ds_read_b128 v[194:197], v228 offset:33792
	ds_read_b128 v[182:185], v228 offset:34816
	ds_read_b128 v[186:189], v228 offset:35840
	ds_read_b128 v[174:177], v228 offset:36864
	ds_read_b128 v[178:181], v228 offset:37888
	ds_read_b128 v[166:169], v228 offset:38912
	ds_read_b128 v[170:173], v228 offset:39936
	s_mov_b64 s[34:35], -1
	s_and_b64 vcc, exec, s[30:31]
	s_cbranch_vccz .LBB0_948
	s_waitcnt vmcnt(0)
	s_mov_b64 s[34:35], 0

.LBB0_950:
	s_waitcnt lgkmcnt(0)
	s_barrier
	s_setprio 1
	s_waitcnt lgkmcnt(0)
	v_mfma_f32_16x16x32_bf16 v[130:133], v[190:193], v[150:153], v[130:133]
	v_mfma_f32_16x16x32_bf16 v[126:129], v[190:193], v[158:161], v[126:129]
	v_mfma_f32_16x16x32_bf16 v[114:117], v[182:185], v[150:153], v[114:117]
	v_mfma_f32_16x16x32_bf16 v[110:113], v[182:185], v[158:161], v[110:113]
	v_mfma_f32_16x16x32_bf16 v[98:101], v[174:177], v[150:153], v[98:101]
	v_mfma_f32_16x16x32_bf16 v[94:97], v[174:177], v[158:161], v[94:97]
	v_mfma_f32_16x16x32_bf16 v[82:85], v[166:169], v[150:153], v[82:85]
	v_mfma_f32_16x16x32_bf16 v[78:81], v[166:169], v[158:161], v[78:81]
	v_mfma_f32_16x16x32_bf16 v[130:133], v[194:197], v[154:157], v[130:133]
	v_mfma_f32_16x16x32_bf16 v[126:129], v[194:197], v[162:165], v[126:129]
	v_mfma_f32_16x16x32_bf16 v[114:117], v[186:189], v[154:157], v[114:117]
	v_mfma_f32_16x16x32_bf16 v[110:113], v[186:189], v[162:165], v[110:113]
	v_mfma_f32_16x16x32_bf16 v[98:101], v[178:181], v[154:157], v[98:101]
	v_mfma_f32_16x16x32_bf16 v[94:97], v[178:181], v[162:165], v[94:97]
	v_mfma_f32_16x16x32_bf16 v[82:85], v[170:173], v[154:157], v[82:85]
	v_mfma_f32_16x16x32_bf16 v[78:81], v[170:173], v[162:165], v[78:81]
	s_setprio 0
	s_setprio 1
	v_mfma_f32_16x16x32_bf16 v[122:125], v[190:193], v[134:137], v[122:125]
	v_mfma_f32_16x16x32_bf16 v[118:121], v[190:193], v[142:145], v[118:121]
	v_mfma_f32_16x16x32_bf16 v[106:109], v[182:185], v[134:137], v[106:109]
	v_mfma_f32_16x16x32_bf16 v[102:105], v[182:185], v[142:145], v[102:105]
	v_mfma_f32_16x16x32_bf16 v[90:93], v[174:177], v[134:137], v[90:93]
	v_mfma_f32_16x16x32_bf16 v[86:89], v[174:177], v[142:145], v[86:89]
	v_mfma_f32_16x16x32_bf16 v[74:77], v[166:169], v[134:137], v[74:77]
	v_mfma_f32_16x16x32_bf16 v[70:73], v[166:169], v[142:145], v[70:73]
	v_mfma_f32_16x16x32_bf16 v[122:125], v[194:197], v[138:141], v[122:125]
	v_mfma_f32_16x16x32_bf16 v[118:121], v[194:197], v[146:149], v[118:121]
	v_mfma_f32_16x16x32_bf16 v[106:109], v[186:189], v[138:141], v[106:109]
	v_mfma_f32_16x16x32_bf16 v[102:105], v[186:189], v[146:149], v[102:105]
	v_mfma_f32_16x16x32_bf16 v[90:93], v[178:181], v[138:141], v[90:93]
	v_mfma_f32_16x16x32_bf16 v[86:89], v[178:181], v[146:149], v[86:89]
	v_mfma_f32_16x16x32_bf16 v[74:77], v[170:173], v[138:141], v[74:77]
	v_mfma_f32_16x16x32_bf16 v[70:73], v[170:173], v[146:149], v[70:73]
	s_setprio 0
	s_barrier
	ds_read_b128 v[190:193], v228 offset:49152
	ds_read_b128 v[194:197], v228 offset:50176
	ds_read_b128 v[182:185], v228 offset:51200
	ds_read_b128 v[186:189], v228 offset:52224
	ds_read_b128 v[174:177], v228 offset:53248
	ds_read_b128 v[178:181], v228 offset:54272
	ds_read_b128 v[166:169], v228 offset:55296
	ds_read_b128 v[170:173], v228 offset:56320
	s_andn2_b64 vcc, exec, s[28:29]
	s_cbranch_vccnz .LBB0_941
	s_mov_b32 m0, s49
	v_lshl_add_u64 v[224:225], v[224:225], 0, s[68:69]
	s_add_u32 s24, s24, 0x1080
	global_load_lds_dwordx4 v[224:225], off
	v_lshl_add_u64 v[222:223], v[222:223], 0, s[68:69]
	s_mov_b32 m0, s50
	s_addc_u32 s25, s25, 0
	global_load_lds_dwordx4 v[222:223], off
	v_lshl_add_u64 v[222:223], s[24:25], 0, v[202:203]
	s_mov_b32 m0, s53
	v_lshl_add_u64 v[220:221], v[220:221], 0, s[68:69]
	global_load_lds_dwordx4 v[222:223], off
	v_lshl_add_u64 v[222:223], s[24:25], 0, v[198:199]
	s_mov_b32 m0, s54
	v_lshl_add_u64 v[218:219], v[218:219], 0, s[68:69]
	global_load_lds_dwordx4 v[222:223], off
	s_mov_b32 m0, s51
	s_nop 0
	global_load_lds_dwordx4 v[220:221], off
	s_mov_b32 m0, s52
	s_nop 0
	global_load_lds_dwordx4 v[218:219], off
	s_waitcnt vmcnt(8)
	s_branch .LBB0_941

.LBB0_958:
	v_bfe_u32 v192, v0, 4, 2
	v_lshlrev_b32_e32 v194, 4, v192
	v_add_u32_e32 v195, 4, v194
	v_add_u32_e32 v196, 8, v194
	v_add_u32_e32 v197, 12, v194
	v_lshlrev_b32_e32 v193, 2, v192
	v_and_b32_e32 v175, -16, v146
	v_add_u32_e32 v175, v175, v193
	v_lshlrev_b32_e32 v175, 13, v175
	v_and_b32_e32 v193, 15, v0
	v_lshlrev_b32_e32 v193, 3, v193
	v_lshrrev_b32_e32 v192, 5, v226
	v_lshl_or_b32 v193, v192, 6, v193
	v_lshl_or_b32 v193, s59, 9, v193
	v_or_b32_e32 v175, v175, v193
	ds_bpermute_b32 v176, v194, v140
	ds_bpermute_b32 v177, v195, v140
	ds_bpermute_b32 v178, v196, v140
	ds_bpermute_b32 v179, v197, v140
	ds_bpermute_b32 v180, v194, v144
	ds_bpermute_b32 v181, v195, v144
	ds_bpermute_b32 v182, v196, v144
	ds_bpermute_b32 v183, v197, v144
	s_waitcnt lgkmcnt(0)
	v_pk_mul_f32 v[126:127], v[126:127], v[176:177]
	v_pk_mul_f32 v[128:129], v[128:129], v[178:179]
	v_pk_mul_f32 v[130:131], v[130:131], v[176:177]
	v_pk_mul_f32 v[132:133], v[132:133], v[178:179]
	v_pk_mul_f32 v[118:119], v[118:119], v[176:177]
	v_pk_mul_f32 v[120:121], v[120:121], v[178:179]
	v_pk_mul_f32 v[122:123], v[122:123], v[176:177]
	v_pk_mul_f32 v[124:125], v[124:125], v[178:179]
	v_pk_mul_f32 v[110:111], v[110:111], v[180:181]
	v_pk_mul_f32 v[112:113], v[112:113], v[182:183]
	v_pk_mul_f32 v[114:115], v[114:115], v[180:181]
	v_pk_mul_f32 v[116:117], v[116:117], v[182:183]
	v_pk_mul_f32 v[102:103], v[102:103], v[180:181]
	v_pk_mul_f32 v[104:105], v[104:105], v[182:183]
	v_pk_mul_f32 v[106:107], v[106:107], v[180:181]
	v_pk_mul_f32 v[108:109], v[108:109], v[182:183]
	s_nop 0
	ds_bpermute_b32 v176, v194, v148
	ds_bpermute_b32 v177, v195, v148
	ds_bpermute_b32 v178, v196, v148
	ds_bpermute_b32 v179, v197, v148
	ds_bpermute_b32 v180, v194, v150
	ds_bpermute_b32 v181, v195, v150
	ds_bpermute_b32 v182, v196, v150
	ds_bpermute_b32 v183, v197, v150
	v_max_f32_e32 v118, 0, v118
	v_max_f32_e32 v119, 0, v119
	v_max_f32_e32 v120, 0, v120
	v_max_f32_e32 v121, 0, v121
	v_max_f32_e32 v122, 0, v122
	v_max_f32_e32 v123, 0, v123
	v_max_f32_e32 v124, 0, v124
	v_max_f32_e32 v125, 0, v125
	v_max_f32_e32 v126, 0, v126
	v_max_f32_e32 v127, 0, v127
	v_max_f32_e32 v128, 0, v128
	v_max_f32_e32 v129, 0, v129
	v_max_f32_e32 v130, 0, v130
	v_max_f32_e32 v131, 0, v131
	v_max_f32_e32 v132, 0, v132
	v_max_f32_e32 v133, 0, v133
	v_pk_mul_f32 v[118:119], v[118:119], v[118:119]
	v_pk_mul_f32 v[120:121], v[120:121], v[120:121]
	v_pk_mul_f32 v[122:123], v[122:123], v[122:123]
	v_pk_mul_f32 v[124:125], v[124:125], v[124:125]
	v_pk_mul_f32 v[126:127], v[126:127], v[126:127]
	v_pk_mul_f32 v[128:129], v[128:129], v[128:129]
	v_pk_mul_f32 v[130:131], v[130:131], v[130:131]
	v_pk_mul_f32 v[132:133], v[132:133], v[132:133]
	v_cvt_pk_bf16_f32 v184, v130, v126
	v_cvt_pk_bf16_f32 v185, v122, v118
	global_store_dwordx2 v175, v[184:185], s[4:5] sc1
	v_cvt_pk_bf16_f32 v186, v131, v127
	v_cvt_pk_bf16_f32 v187, v123, v119
	v_add_u32_e32 v192, 0x2000, v175
	global_store_dwordx2 v192, v[186:187], s[4:5] sc1
	v_cvt_pk_bf16_f32 v188, v132, v128
	v_cvt_pk_bf16_f32 v189, v124, v120
	v_add_u32_e32 v193, 0x4000, v175
	global_store_dwordx2 v193, v[188:189], s[4:5] sc1
	v_cvt_pk_bf16_f32 v190, v133, v129
	v_cvt_pk_bf16_f32 v191, v125, v121
	v_add_u32_e32 v2, 0x6000, v175
	global_store_dwordx2 v2, v[190:191], s[4:5] sc1
	v_max_f32_e32 v102, 0, v102
	v_max_f32_e32 v103, 0, v103
	v_max_f32_e32 v104, 0, v104
	v_max_f32_e32 v105, 0, v105
	v_max_f32_e32 v106, 0, v106
	v_max_f32_e32 v107, 0, v107
	v_max_f32_e32 v108, 0, v108
	v_max_f32_e32 v109, 0, v109
	v_max_f32_e32 v110, 0, v110
	v_max_f32_e32 v111, 0, v111
	v_max_f32_e32 v112, 0, v112
	v_max_f32_e32 v113, 0, v113
	v_max_f32_e32 v114, 0, v114
	v_max_f32_e32 v115, 0, v115
	v_max_f32_e32 v116, 0, v116
	v_max_f32_e32 v117, 0, v117
	v_pk_mul_f32 v[102:103], v[102:103], v[102:103]
	v_pk_mul_f32 v[104:105], v[104:105], v[104:105]
	v_pk_mul_f32 v[106:107], v[106:107], v[106:107]
	v_pk_mul_f32 v[108:109], v[108:109], v[108:109]
	v_pk_mul_f32 v[110:111], v[110:111], v[110:111]
	v_pk_mul_f32 v[112:113], v[112:113], v[112:113]
	v_pk_mul_f32 v[114:115], v[114:115], v[114:115]
	v_pk_mul_f32 v[116:117], v[116:117], v[116:117]
	v_cvt_pk_bf16_f32 v184, v114, v110
	v_cvt_pk_bf16_f32 v185, v106, v102
	v_add_u32_e32 v3, 0x20000, v175
	global_store_dwordx2 v3, v[184:185], s[4:5] sc1
	v_cvt_pk_bf16_f32 v186, v115, v111
	v_cvt_pk_bf16_f32 v187, v107, v103
	v_add_u32_e32 v192, 0x22000, v175
	global_store_dwordx2 v192, v[186:187], s[4:5] sc1
	v_cvt_pk_bf16_f32 v188, v116, v112
	v_cvt_pk_bf16_f32 v189, v108, v104
	v_add_u32_e32 v193, 0x24000, v175
	global_store_dwordx2 v193, v[188:189], s[4:5] sc1
	v_cvt_pk_bf16_f32 v190, v117, v113
	v_cvt_pk_bf16_f32 v191, v109, v105
	v_add_u32_e32 v2, 0x26000, v175
	global_store_dwordx2 v2, v[190:191], s[4:5] sc1
	s_waitcnt lgkmcnt(0)
	v_pk_mul_f32 v[94:95], v[94:95], v[176:177]
	v_pk_mul_f32 v[96:97], v[96:97], v[178:179]
	v_pk_mul_f32 v[98:99], v[98:99], v[176:177]
	v_pk_mul_f32 v[100:101], v[100:101], v[178:179]
	v_pk_mul_f32 v[86:87], v[86:87], v[176:177]
	v_pk_mul_f32 v[88:89], v[88:89], v[178:179]
	v_pk_mul_f32 v[90:91], v[90:91], v[176:177]
	v_pk_mul_f32 v[92:93], v[92:93], v[178:179]
	v_pk_mul_f32 v[78:79], v[78:79], v[180:181]
	v_pk_mul_f32 v[80:81], v[80:81], v[182:183]
	v_pk_mul_f32 v[82:83], v[82:83], v[180:181]
	v_pk_mul_f32 v[84:85], v[84:85], v[182:183]
	v_pk_mul_f32 v[70:71], v[70:71], v[180:181]
	v_pk_mul_f32 v[72:73], v[72:73], v[182:183]
	v_pk_mul_f32 v[74:75], v[74:75], v[180:181]
	v_pk_mul_f32 v[76:77], v[76:77], v[182:183]
	s_nop 0
	ds_bpermute_b32 v176, v194, v136
	ds_bpermute_b32 v177, v195, v136
	ds_bpermute_b32 v178, v196, v136
	ds_bpermute_b32 v179, v197, v136
	ds_bpermute_b32 v180, v194, v137
	ds_bpermute_b32 v181, v195, v137
	ds_bpermute_b32 v182, v196, v137
	ds_bpermute_b32 v183, v197, v137
	v_max_f32_e32 v86, 0, v86
	v_max_f32_e32 v87, 0, v87
	v_max_f32_e32 v88, 0, v88
	v_max_f32_e32 v89, 0, v89
	v_max_f32_e32 v90, 0, v90
	v_max_f32_e32 v91, 0, v91
	v_max_f32_e32 v92, 0, v92
	v_max_f32_e32 v93, 0, v93
	v_max_f32_e32 v94, 0, v94
	v_max_f32_e32 v95, 0, v95
	v_max_f32_e32 v96, 0, v96
	v_max_f32_e32 v97, 0, v97
	v_max_f32_e32 v98, 0, v98
	v_max_f32_e32 v99, 0, v99
	v_max_f32_e32 v100, 0, v100
	v_max_f32_e32 v101, 0, v101
	v_pk_mul_f32 v[86:87], v[86:87], v[86:87]
	v_pk_mul_f32 v[88:89], v[88:89], v[88:89]
	v_pk_mul_f32 v[90:91], v[90:91], v[90:91]
	v_pk_mul_f32 v[92:93], v[92:93], v[92:93]
	v_pk_mul_f32 v[94:95], v[94:95], v[94:95]
	v_pk_mul_f32 v[96:97], v[96:97], v[96:97]
	v_pk_mul_f32 v[98:99], v[98:99], v[98:99]
	v_pk_mul_f32 v[100:101], v[100:101], v[100:101]
	v_cvt_pk_bf16_f32 v184, v98, v94
	v_cvt_pk_bf16_f32 v185, v90, v86
	v_add_u32_e32 v3, 0x40000, v175
	global_store_dwordx2 v3, v[184:185], s[4:5] sc1
	v_cvt_pk_bf16_f32 v186, v99, v95
	v_cvt_pk_bf16_f32 v187, v91, v87
	v_add_u32_e32 v192, 0x42000, v175
	global_store_dwordx2 v192, v[186:187], s[4:5] sc1
	v_cvt_pk_bf16_f32 v188, v100, v96
	v_cvt_pk_bf16_f32 v189, v92, v88
	v_add_u32_e32 v193, 0x44000, v175
	global_store_dwordx2 v193, v[188:189], s[4:5] sc1
	v_cvt_pk_bf16_f32 v190, v101, v97
	v_cvt_pk_bf16_f32 v191, v93, v89
	v_add_u32_e32 v2, 0x46000, v175
	global_store_dwordx2 v2, v[190:191], s[4:5] sc1
	v_max_f32_e32 v70, 0, v70
	v_max_f32_e32 v71, 0, v71
	v_max_f32_e32 v72, 0, v72
	v_max_f32_e32 v73, 0, v73
	v_max_f32_e32 v74, 0, v74
	v_max_f32_e32 v75, 0, v75
	v_max_f32_e32 v76, 0, v76
	v_max_f32_e32 v77, 0, v77
	v_max_f32_e32 v78, 0, v78
	v_max_f32_e32 v79, 0, v79
	v_max_f32_e32 v80, 0, v80
	v_max_f32_e32 v81, 0, v81
	v_max_f32_e32 v82, 0, v82
	v_max_f32_e32 v83, 0, v83
	v_max_f32_e32 v84, 0, v84
	v_max_f32_e32 v85, 0, v85
	v_pk_mul_f32 v[70:71], v[70:71], v[70:71]
	v_pk_mul_f32 v[72:73], v[72:73], v[72:73]
	v_pk_mul_f32 v[74:75], v[74:75], v[74:75]
	v_pk_mul_f32 v[76:77], v[76:77], v[76:77]
	v_pk_mul_f32 v[78:79], v[78:79], v[78:79]
	v_pk_mul_f32 v[80:81], v[80:81], v[80:81]
	v_pk_mul_f32 v[82:83], v[82:83], v[82:83]
	v_pk_mul_f32 v[84:85], v[84:85], v[84:85]
	v_cvt_pk_bf16_f32 v184, v82, v78
	v_cvt_pk_bf16_f32 v185, v74, v70
	v_add_u32_e32 v3, 0x60000, v175
	global_store_dwordx2 v3, v[184:185], s[4:5] sc1
	v_cvt_pk_bf16_f32 v186, v83, v79
	v_cvt_pk_bf16_f32 v187, v75, v71
	v_add_u32_e32 v192, 0x62000, v175
	global_store_dwordx2 v192, v[186:187], s[4:5] sc1
	v_cvt_pk_bf16_f32 v188, v84, v80
	v_cvt_pk_bf16_f32 v189, v76, v72
	v_add_u32_e32 v193, 0x64000, v175
	global_store_dwordx2 v193, v[188:189], s[4:5] sc1
	v_cvt_pk_bf16_f32 v190, v85, v81
	v_cvt_pk_bf16_f32 v191, v77, v73
	v_add_u32_e32 v2, 0x66000, v175
	global_store_dwordx2 v2, v[190:191], s[4:5] sc1
	s_waitcnt lgkmcnt(0)
	v_pk_mul_f32 v[62:63], v[62:63], v[176:177]
	v_pk_mul_f32 v[64:65], v[64:65], v[178:179]
	v_pk_mul_f32 v[66:67], v[66:67], v[176:177]
	v_pk_mul_f32 v[68:69], v[68:69], v[178:179]
	v_pk_mul_f32 v[54:55], v[54:55], v[176:177]
	v_pk_mul_f32 v[56:57], v[56:57], v[178:179]
	v_pk_mul_f32 v[58:59], v[58:59], v[176:177]
	v_pk_mul_f32 v[60:61], v[60:61], v[178:179]
	v_pk_mul_f32 v[46:47], v[46:47], v[180:181]
	v_pk_mul_f32 v[48:49], v[48:49], v[182:183]
	v_pk_mul_f32 v[50:51], v[50:51], v[180:181]
	v_pk_mul_f32 v[52:53], v[52:53], v[182:183]
	v_pk_mul_f32 v[38:39], v[38:39], v[180:181]
	v_pk_mul_f32 v[40:41], v[40:41], v[182:183]
	v_pk_mul_f32 v[42:43], v[42:43], v[180:181]
	v_pk_mul_f32 v[44:45], v[44:45], v[182:183]
	s_nop 0
	ds_bpermute_b32 v176, v194, v152
	ds_bpermute_b32 v177, v195, v152
	ds_bpermute_b32 v178, v196, v152
	ds_bpermute_b32 v179, v197, v152
	ds_bpermute_b32 v180, v194, v154
	ds_bpermute_b32 v181, v195, v154
	ds_bpermute_b32 v182, v196, v154
	ds_bpermute_b32 v183, v197, v154
	v_max_f32_e32 v54, 0, v54
	v_max_f32_e32 v55, 0, v55
	v_max_f32_e32 v56, 0, v56
	v_max_f32_e32 v57, 0, v57
	v_max_f32_e32 v58, 0, v58
	v_max_f32_e32 v59, 0, v59
	v_max_f32_e32 v60, 0, v60
	v_max_f32_e32 v61, 0, v61
	v_max_f32_e32 v62, 0, v62
	v_max_f32_e32 v63, 0, v63
	v_max_f32_e32 v64, 0, v64
	v_max_f32_e32 v65, 0, v65
	v_max_f32_e32 v66, 0, v66
	v_max_f32_e32 v67, 0, v67
	v_max_f32_e32 v68, 0, v68
	v_max_f32_e32 v69, 0, v69
	v_pk_mul_f32 v[54:55], v[54:55], v[54:55]
	v_pk_mul_f32 v[56:57], v[56:57], v[56:57]
	v_pk_mul_f32 v[58:59], v[58:59], v[58:59]
	v_pk_mul_f32 v[60:61], v[60:61], v[60:61]
	v_pk_mul_f32 v[62:63], v[62:63], v[62:63]
	v_pk_mul_f32 v[64:65], v[64:65], v[64:65]
	v_pk_mul_f32 v[66:67], v[66:67], v[66:67]
	v_pk_mul_f32 v[68:69], v[68:69], v[68:69]
	v_cvt_pk_bf16_f32 v184, v66, v62
	v_cvt_pk_bf16_f32 v185, v58, v54
	v_add_u32_e32 v3, 0x100000, v175
	global_store_dwordx2 v3, v[184:185], s[4:5] sc1
	v_cvt_pk_bf16_f32 v186, v67, v63
	v_cvt_pk_bf16_f32 v187, v59, v55
	v_add_u32_e32 v192, 0x102000, v175
	global_store_dwordx2 v192, v[186:187], s[4:5] sc1
	v_cvt_pk_bf16_f32 v188, v68, v64
	v_cvt_pk_bf16_f32 v189, v60, v56
	v_add_u32_e32 v193, 0x104000, v175
	global_store_dwordx2 v193, v[188:189], s[4:5] sc1
	v_cvt_pk_bf16_f32 v190, v69, v65
	v_cvt_pk_bf16_f32 v191, v61, v57
	v_add_u32_e32 v2, 0x106000, v175
	global_store_dwordx2 v2, v[190:191], s[4:5] sc1
	v_max_f32_e32 v38, 0, v38
	v_max_f32_e32 v39, 0, v39
	v_max_f32_e32 v40, 0, v40
	v_max_f32_e32 v41, 0, v41
	v_max_f32_e32 v42, 0, v42
	v_max_f32_e32 v43, 0, v43
	v_max_f32_e32 v44, 0, v44
	v_max_f32_e32 v45, 0, v45
	v_max_f32_e32 v46, 0, v46
	v_max_f32_e32 v47, 0, v47
	v_max_f32_e32 v48, 0, v48
	v_max_f32_e32 v49, 0, v49
	v_max_f32_e32 v50, 0, v50
	v_max_f32_e32 v51, 0, v51
	v_max_f32_e32 v52, 0, v52
	v_max_f32_e32 v53, 0, v53
	v_pk_mul_f32 v[38:39], v[38:39], v[38:39]
	v_pk_mul_f32 v[40:41], v[40:41], v[40:41]
	v_pk_mul_f32 v[42:43], v[42:43], v[42:43]
	v_pk_mul_f32 v[44:45], v[44:45], v[44:45]
	v_pk_mul_f32 v[46:47], v[46:47], v[46:47]
	v_pk_mul_f32 v[48:49], v[48:49], v[48:49]
	v_pk_mul_f32 v[50:51], v[50:51], v[50:51]
	v_pk_mul_f32 v[52:53], v[52:53], v[52:53]
	v_cvt_pk_bf16_f32 v184, v50, v46
	v_cvt_pk_bf16_f32 v185, v42, v38
	v_add_u32_e32 v3, 0x120000, v175
	global_store_dwordx2 v3, v[184:185], s[4:5] sc1
	v_cvt_pk_bf16_f32 v186, v51, v47
	v_cvt_pk_bf16_f32 v187, v43, v39
	v_add_u32_e32 v192, 0x122000, v175
	global_store_dwordx2 v192, v[186:187], s[4:5] sc1
	v_cvt_pk_bf16_f32 v188, v52, v48
	v_cvt_pk_bf16_f32 v189, v44, v40
	v_add_u32_e32 v193, 0x124000, v175
	global_store_dwordx2 v193, v[188:189], s[4:5] sc1
	v_cvt_pk_bf16_f32 v190, v53, v49
	v_cvt_pk_bf16_f32 v191, v45, v41
	v_add_u32_e32 v2, 0x126000, v175
	global_store_dwordx2 v2, v[190:191], s[4:5] sc1
	s_waitcnt lgkmcnt(0)
	v_pk_mul_f32 v[30:31], v[30:31], v[176:177]
	v_pk_mul_f32 v[32:33], v[32:33], v[178:179]
	v_pk_mul_f32 v[34:35], v[34:35], v[176:177]
	v_pk_mul_f32 v[36:37], v[36:37], v[178:179]
	v_pk_mul_f32 v[22:23], v[22:23], v[176:177]
	v_pk_mul_f32 v[24:25], v[24:25], v[178:179]
	v_pk_mul_f32 v[26:27], v[26:27], v[176:177]
	v_pk_mul_f32 v[28:29], v[28:29], v[178:179]
	v_pk_mul_f32 v[14:15], v[14:15], v[180:181]
	v_pk_mul_f32 v[16:17], v[16:17], v[182:183]
	v_pk_mul_f32 v[18:19], v[18:19], v[180:181]
	v_pk_mul_f32 v[20:21], v[20:21], v[182:183]
	v_pk_mul_f32 v[6:7], v[6:7], v[180:181]
	v_pk_mul_f32 v[8:9], v[8:9], v[182:183]
	v_pk_mul_f32 v[10:11], v[10:11], v[180:181]
	v_pk_mul_f32 v[12:13], v[12:13], v[182:183]
	v_max_f32_e32 v22, 0, v22
	v_max_f32_e32 v23, 0, v23
	v_max_f32_e32 v24, 0, v24
	v_max_f32_e32 v25, 0, v25
	v_max_f32_e32 v26, 0, v26
	v_max_f32_e32 v27, 0, v27
	v_max_f32_e32 v28, 0, v28
	v_max_f32_e32 v29, 0, v29
	v_max_f32_e32 v30, 0, v30
	v_max_f32_e32 v31, 0, v31
	v_max_f32_e32 v32, 0, v32
	v_max_f32_e32 v33, 0, v33
	v_max_f32_e32 v34, 0, v34
	v_max_f32_e32 v35, 0, v35
	v_max_f32_e32 v36, 0, v36
	v_max_f32_e32 v37, 0, v37
	v_pk_mul_f32 v[22:23], v[22:23], v[22:23]
	v_pk_mul_f32 v[24:25], v[24:25], v[24:25]
	v_pk_mul_f32 v[26:27], v[26:27], v[26:27]
	v_pk_mul_f32 v[28:29], v[28:29], v[28:29]
	v_pk_mul_f32 v[30:31], v[30:31], v[30:31]
	v_pk_mul_f32 v[32:33], v[32:33], v[32:33]
	v_pk_mul_f32 v[34:35], v[34:35], v[34:35]
	v_pk_mul_f32 v[36:37], v[36:37], v[36:37]
	v_cvt_pk_bf16_f32 v184, v34, v30
	v_cvt_pk_bf16_f32 v185, v26, v22
	v_add_u32_e32 v3, 0x140000, v175
	global_store_dwordx2 v3, v[184:185], s[4:5] sc1
	v_cvt_pk_bf16_f32 v186, v35, v31
	v_cvt_pk_bf16_f32 v187, v27, v23
	v_add_u32_e32 v192, 0x142000, v175
	global_store_dwordx2 v192, v[186:187], s[4:5] sc1
	v_cvt_pk_bf16_f32 v188, v36, v32
	v_cvt_pk_bf16_f32 v189, v28, v24
	v_add_u32_e32 v193, 0x144000, v175
	global_store_dwordx2 v193, v[188:189], s[4:5] sc1
	v_cvt_pk_bf16_f32 v190, v37, v33
	v_cvt_pk_bf16_f32 v191, v29, v25
	v_add_u32_e32 v2, 0x146000, v175
	global_store_dwordx2 v2, v[190:191], s[4:5] sc1
	v_max_f32_e32 v6, 0, v6
	v_max_f32_e32 v7, 0, v7
	v_max_f32_e32 v8, 0, v8
	v_max_f32_e32 v9, 0, v9
	v_max_f32_e32 v10, 0, v10
	v_max_f32_e32 v11, 0, v11
	v_max_f32_e32 v12, 0, v12
	v_max_f32_e32 v13, 0, v13
	v_max_f32_e32 v14, 0, v14
	v_max_f32_e32 v15, 0, v15
	v_max_f32_e32 v16, 0, v16
	v_max_f32_e32 v17, 0, v17
	v_max_f32_e32 v18, 0, v18
	v_max_f32_e32 v19, 0, v19
	v_max_f32_e32 v20, 0, v20
	v_max_f32_e32 v21, 0, v21
	v_pk_mul_f32 v[6:7], v[6:7], v[6:7]
	v_pk_mul_f32 v[8:9], v[8:9], v[8:9]
	v_pk_mul_f32 v[10:11], v[10:11], v[10:11]
	v_pk_mul_f32 v[12:13], v[12:13], v[12:13]
	v_pk_mul_f32 v[14:15], v[14:15], v[14:15]
	v_pk_mul_f32 v[16:17], v[16:17], v[16:17]
	v_pk_mul_f32 v[18:19], v[18:19], v[18:19]
	v_pk_mul_f32 v[20:21], v[20:21], v[20:21]
	v_cvt_pk_bf16_f32 v184, v18, v14
	v_cvt_pk_bf16_f32 v185, v10, v6
	v_add_u32_e32 v3, 0x160000, v175
	global_store_dwordx2 v3, v[184:185], s[4:5] sc1
	v_cvt_pk_bf16_f32 v186, v19, v15
	v_cvt_pk_bf16_f32 v187, v11, v7
	v_add_u32_e32 v192, 0x162000, v175
	global_store_dwordx2 v192, v[186:187], s[4:5] sc1
	v_cvt_pk_bf16_f32 v188, v20, v16
	v_cvt_pk_bf16_f32 v189, v12, v8
	v_add_u32_e32 v193, 0x164000, v175
	global_store_dwordx2 v193, v[188:189], s[4:5] sc1
	v_cvt_pk_bf16_f32 v190, v21, v17
	v_cvt_pk_bf16_f32 v191, v13, v9
	v_add_u32_e32 v2, 0x166000, v175
	global_store_dwordx2 v2, v[190:191], s[4:5] sc1
	s_andn2_b64 vcc, exec, s[20:21]
	s_mov_b64 s[20:21], -1
	s_cbranch_vccnz .LBB0_936
	s_andn2_b64 vcc, exec, s[2:3]
	s_cbranch_vccnz .LBB0_935
	s_barrier
	s_branch .LBB0_935
